# v26 with 128-byte instead of 64-byte alignment of the five K-loop bodies
# speedup vs baseline: 1.0098x; 1.0011x over previous
.LBB0_260:
	s_ashr_i32 s65, s64, 31
	s_lshl_b64 s[22:23], s[64:65], 20
	s_add_u32 s62, s79, s22
	s_addc_u32 s63, s28, s23
	s_and_b64 s[22:23], s[4:5], exec
	s_cselect_b32 s22, s63, s77
	s_cselect_b32 s23, s62, s76
	s_ashr_i32 s49, s48, 31
	s_lshl_b64 s[70:71], s[48:49], 20
	s_add_u32 s70, s8, s70
	s_addc_u32 s71, s9, s71
	s_and_b64 s[90:91], s[4:5], exec
	s_cselect_b32 s49, s71, s85
	s_cselect_b32 s57, s70, s84
	s_ashr_i32 s51, s50, 31
	s_lshl_b32 s90, s44, 8
	s_lshl_b64 vcc, s[50:51], 10
	s_ashr_i32 s0, s50, 5
	s_ashr_i32 s91, s90, 31
	s_add_u32 s76, s76, 0x80080
	v_lshl_add_u64 v[2:3], s[90:91], 2, v[134:135]
	v_mov_b32_e32 v4, 0x6000
	s_addc_u32 s77, s77, 0
	v_lshl_add_u64 v[142:143], v[136:137], 0, vcc
	v_mad_i64_i32 v[144:145], vcc, s0, v4, v[2:3]
	s_add_u32 s51, s84, 0x100
	s_addc_u32 s58, s85, 0
	s_mov_b32 s65, -2
	s_branch .LBB0_262
	.p2align	7

.LBB0_284:
	s_ashr_i32 s49, s48, 31
	s_lshl_b64 s[22:23], s[48:49], 20
	s_add_u32 s50, s79, s22
	s_addc_u32 s51, s28, s23
	s_and_b64 s[22:23], s[4:5], exec
	s_cselect_b32 s21, s51, s77
	s_cselect_b32 s22, s50, s76
	s_ashr_i32 s39, s38, 31
	s_lshl_b64 s[62:63], s[38:39], 20
	s_add_u32 s62, s29, s62
	s_addc_u32 s63, s31, s63
	s_and_b64 s[64:65], s[4:5], exec
	s_cselect_b32 s23, s63, s71
	s_cselect_b32 s39, s62, s70
	s_ashr_i32 s7, s6, 31
	s_lshl_b32 s64, s40, 8
	s_lshl_b64 vcc, s[6:7], 10
	s_ashr_i32 s0, s6, 5
	s_ashr_i32 s65, s64, 31
	s_add_u32 s76, s76, 0x80080
	v_lshl_add_u64 v[2:3], s[64:65], 2, v[166:167]
	v_mov_b32_e32 v4, 0x5800
	s_addc_u32 s77, s77, 0
	v_lshl_add_u64 v[130:131], v[168:169], 0, vcc
	v_mad_i64_i32 v[132:133], vcc, s0, v4, v[2:3]
	s_add_u32 s7, s70, 0x100
	s_addc_u32 s41, s71, 0
	s_mov_b32 s43, -2
	s_branch .LBB0_286
	.p2align	7

.LBB0_508:
	s_ashr_i32 s53, s52, 31
	s_lshl_b64 s[0:1], s[52:53], 20
	s_add_u32 s62, s20, s0
	s_addc_u32 s63, s21, s1
	s_and_b64 s[0:1], s[6:7], exec
	s_cselect_b32 s22, s63, s77
	s_cselect_b32 s23, s62, s76
	s_ashr_i32 s51, s50, 31
	s_lshl_b64 s[0:1], s[50:51], 20
	s_add_u32 s84, s26, s0
	s_addc_u32 s85, s27, s1
	s_and_b64 s[0:1], s[6:7], exec
	s_cselect_b32 s41, s85, s91
	s_cselect_b32 s44, s84, s90
	s_lshl_b32 s64, s57, 8
	s_ashr_i32 s65, s64, 31
	s_lshl_b64 s[0:1], s[64:65], 2
	s_ashr_i32 s18, s40, 5
	v_lshl_add_u64 v[2:3], v[206:207], 0, s[0:1]
	v_lshl_add_u64 v[4:5], v[208:209], 0, s[0:1]
	v_mad_i64_i32 v[70:71], s[0:1], s18, v235, v[2:3]
	s_add_u32 s51, s90, 0x100
	v_mad_i64_i32 v[72:73], s[0:1], s18, v235, v[4:5]
	s_addc_u32 s53, s91, 0
	s_mov_b32 s57, -2
	s_branch .LBB0_510
	.p2align	7

.LBB0_580:
	s_ashr_i32 s47, s46, 31
	s_lshl_b64 s[0:1], s[46:47], 20
	s_add_u32 s48, s20, s0
	s_addc_u32 s49, s21, s1
	s_and_b64 s[0:1], s[6:7], exec
	s_cselect_b32 s22, s49, s63
	s_cselect_b32 s23, s48, s62
	s_ashr_i32 s39, s38, 31
	s_lshl_b64 s[0:1], s[38:39], 20
	s_add_u32 s50, s26, s0
	s_addc_u32 s51, s27, s1
	s_and_b64 s[0:1], s[6:7], exec
	s_cselect_b32 s39, s51, s65
	s_cselect_b32 s47, s50, s64
	s_ashr_i32 s53, s52, 31
	s_lshl_b32 s18, s44, 8
	s_lshl_b64 s[0:1], s[52:53], 10
	s_ashr_i32 s24, s52, 5
	s_ashr_i32 s19, s18, 31
	s_add_u32 s62, s62, 0x80080
	v_lshl_add_u64 v[2:3], s[18:19], 2, v[132:133]
	s_addc_u32 s63, s63, 0
	v_lshl_add_u64 v[140:141], v[134:135], 0, s[0:1]
	v_mad_i64_i32 v[142:143], s[0:1], s24, v236, v[2:3]
	s_add_u32 s53, s64, 0x100
	s_addc_u32 s58, s65, 0
	s_mov_b32 s76, -2
	s_branch .LBB0_582
	.p2align	7

.LBB0_644:
	s_lshl_b32 s6, s23, 8
	s_ashr_i32 s7, s6, 31
	s_lshl_b64 s[0:1], s[6:7], 2
	s_ashr_i32 s24, s22, 5
	v_lshl_add_u64 v[2:3], v[204:205], 0, s[0:1]
	v_mad_i64_i32 v[66:67], s[18:19], s24, v235, v[2:3]
	s_mul_hi_i32 s7, s24, 0xc000
	s_mul_i32 s24, s24, 0xc000
	s_add_u32 s18, s90, s24
	s_addc_u32 s7, s80, s7
	s_add_u32 s0, s18, s0
	s_addc_u32 s1, s7, s1
	s_add_u32 s7, s64, 0x100
	v_lshl_add_u64 v[68:69], s[0:1], 0, v[194:195]
	s_addc_u32 s23, s65, 0
	s_mov_b32 s41, -2
	s_branch .LBB0_646
	.p2align	7
